# step 0: the eight K0 fragment reads issued up front (were six serialized LDS round trips through one register quad)
# speedup vs baseline: 1.0064x; 1.0018x over previous
;   #define CINIT(C0,C1,btl) do{ const float b_=(btl); _Pragma("unroll") for(int r=0;r<16;++r){ C0[r]=__builtin_fmaf(s2,(float)((r&3)+8*(r>>2)),b_); C1[r]=__builtin_fmaf(s2,(float)((r&3)+8*(r>>2)+32),b_);} }while(0)
;   #define CMASK(P0,P1,t) do{ if(WIN||(t)>=NT-4)gmask(P0,P1,64*(t),qrel,hi,WIN);}while(0)
;   #define CMASK(P0,P1,t) do{}while(0)
;   #define CMASK(P0,P1,t) do{ if(WIN||(t)>=NT-4)gmask(P0,P1,64*(t),qrel,hi,WIN);}while(0)
; __device__ __forceinline__ void qkt(f32x16&p0,f32x16&p1,const char*Kslot,const bf16x8*qr,int r32,int hi){
;   const char*kb=Kslot+hi*1024+r32*16;
;   #pragma unroll
;   for(int d0=0;d0<4;++d0){
;     const bf16x8 b0=*reinterpret_cast<const bf16x8*>(kb+d0*2048);
;     const bf16x8 b1=*reinterpret_cast<const bf16x8*>(kb+d0*2048+512);
;     p0=__builtin_amdgcn_mfma_f32_32x32x16_bf16(b0,qr[d0],p0,0,0,0);p1=__builtin_amdgcn_mfma_f32_32x32x16_bf16(b1,qr[d0],p1,0,0,0);}
; }
; template<int THRL> __device__ __forceinline__ void attn_unit(long rowbase,int qb,int t0,bool WIN,bool NOMAX,const bf16*Qc,const bf16*__restrict__ Kc,const bf16*__restrict__ Vc,bf16*Oc,float s2,float sink2,char*shm,
;     bf16x8 (&qr)[4],bool pref,const bf16*qkvb,int vn,int in_){
;     ...
;   CINIT(pA0,pA1,-qb2); qkt(pA0,pA1,Kbase,qr,r32,hi);asm volatile("s_nop 15\n\ts_nop 7":"+v"(pA0),"+v"(pA1));CMASK(pA0,pA1,0);
.LBB0_265:
	s_sub_i32 s38, s4, s45
	v_or_b32_e32 v18, s38, v180
	v_lshlrev_b32_e32 v230, 2, v181
	v_add_u32_e32 v223, s2, v18
	v_sub_u32_e32 v18, v223, v230
	v_cvt_f32_i32_e32 v19, v18
	v_lshlrev_b32_e32 v18, 10, v181
	v_lshlrev_b32_e32 v20, 4, v180
	v_add3_u32 v231, 0, v18, v20
	v_mul_f32_e32 v184, 0x3fb8aa3b, v34
	ds_read_b128 v[34:37], v231
	ds_read_b128 v[52:55], v231 offset:512
	ds_read_b128 v[56:59], v231 offset:2048
	ds_read_b128 v[60:63], v231 offset:2560
	ds_read_b128 v[64:67], v231 offset:4096
	ds_read_b128 v[68:71], v231 offset:4608
	ds_read_b128 v[72:75], v231 offset:6144
	ds_read_b128 v[76:79], v231 offset:6656
	v_mul_f32_e64 v186, v184, -v19
	v_fma_f32 v18, 0, v184, v186
	v_fma_f32 v19, v184, -v19, v184
	v_pk_fma_f32 v[20:21], v[184:185], s[8:9], v[186:187] op_sel_hi:[0,1,0]
	v_pk_fma_f32 v[22:23], v[184:185], s[10:11], v[186:187] op_sel_hi:[0,1,0]
	v_pk_fma_f32 v[24:25], v[184:185], s[12:13], v[186:187] op_sel_hi:[0,1,0]
	v_pk_fma_f32 v[26:27], v[184:185], s[14:15], v[186:187] op_sel_hi:[0,1,0]
	v_pk_fma_f32 v[28:29], v[184:185], s[16:17], v[186:187] op_sel_hi:[0,1,0]
	v_pk_fma_f32 v[30:31], v[184:185], s[18:19], v[186:187] op_sel_hi:[0,1,0]
	v_pk_fma_f32 v[32:33], v[184:185], s[20:21], v[186:187] op_sel_hi:[0,1,0]
	v_pk_fma_f32 v[48:49], v[184:185], s[22:23], v[186:187] op_sel_hi:[0,1,0]
	v_pk_fma_f32 v[46:47], v[184:185], s[24:25], v[186:187] op_sel_hi:[0,1,0]
	s_waitcnt vmcnt(3) lgkmcnt(7)
	v_mfma_f32_32x32x16_bf16 v[18:33], v[34:37], v[2:5], v[18:33]
	v_fma_f32 v44, v184, s26, v186
	v_fma_f32 v45, v184, s27, v186
	v_fma_f32 v42, v184, s28, v186
	v_fma_f32 v43, v184, s29, v186
	v_fma_f32 v40, v184, s30, v186
	v_fma_f32 v41, v184, s31, v186
	v_pk_fma_f32 v[38:39], v[184:185], s[34:35], v[186:187] op_sel_hi:[0,1,0]
	v_pk_fma_f32 v[36:37], v[184:185], s[36:37], v[186:187] op_sel_hi:[0,1,0]
	v_pk_fma_f32 v[34:35], v[184:185], s[92:93], v[186:187] op_sel_hi:[0,1,0]
	s_addk_i32 s4, 0x100
	s_lshr_b32 s4, s4, 6
	s_waitcnt lgkmcnt(6)
	v_mfma_f32_32x32x16_bf16 v[34:49], v[52:55], v[2:5], v[34:49]
	s_sub_i32 s4, s4, s48
	s_cmp_lg_u32 s62, 0
	s_cselect_b32 s4, 4, s4
	s_cmp_lt_i32 s4, 5
	s_cselect_b64 s[38:39], -1, 0
	s_or_b64 s[38:39], s[62:63], s[38:39]
	s_andn2_b64 vcc, exec, s[38:39]
	v_add_u32_e32 v224, 0xffffff80, v223
	s_waitcnt vmcnt(2) lgkmcnt(5)
	v_mfma_f32_32x32x16_bf16 v[18:33], v[56:59], v[6:9], v[18:33]
	s_waitcnt lgkmcnt(4)
	v_mfma_f32_32x32x16_bf16 v[34:49], v[60:63], v[6:9], v[34:49]
	s_waitcnt vmcnt(1) lgkmcnt(3)
	v_mfma_f32_32x32x16_bf16 v[18:33], v[64:67], v[10:13], v[18:33]
	s_waitcnt lgkmcnt(2)
	v_mfma_f32_32x32x16_bf16 v[34:49], v[68:71], v[10:13], v[34:49]
	s_waitcnt vmcnt(0) lgkmcnt(1)
	v_mfma_f32_32x32x16_bf16 v[18:33], v[72:75], v[14:17], v[18:33]
	s_waitcnt lgkmcnt(0)
	v_mfma_f32_32x32x16_bf16 v[34:49], v[76:79], v[14:17], v[34:49]
	v_cndmask_b32_e64 v52, 0, 1, s[62:63]
	v_cmp_ne_u32_e64 s[38:39], 1, v52
	s_nop 15
	s_nop 7
	s_cbranch_vccnz .LBB0_330
	v_sub_u32_e32 v52, v223, v230
	s_nop 0
	v_readfirstlane_b32 s40, v52
	s_cmp_gt_i32 s40, 66
	s_cbranch_scc1 .Lmy_mk_c_s0
	v_cmp_le_i32_e32 vcc, 0, v52
	v_cndmask_b32_e32 v18, v217, v18, vcc
	v_cmp_le_i32_e32 vcc, 32, v52
	v_cndmask_b32_e32 v34, v217, v34, vcc
	v_cmp_le_i32_e32 vcc, 1, v52
	v_cndmask_b32_e32 v19, v217, v19, vcc
	v_cmp_le_i32_e32 vcc, 33, v52
	v_cndmask_b32_e32 v35, v217, v35, vcc
	v_cmp_le_i32_e32 vcc, 2, v52
	v_cndmask_b32_e32 v20, v217, v20, vcc
	v_cmp_le_i32_e32 vcc, 34, v52
	v_cndmask_b32_e32 v36, v217, v36, vcc
	v_cmp_le_i32_e32 vcc, 3, v52
	v_cndmask_b32_e32 v21, v217, v21, vcc
	v_cmp_le_i32_e32 vcc, 35, v52
	v_cndmask_b32_e32 v37, v217, v37, vcc
	v_cmp_le_i32_e32 vcc, 8, v52
	v_cndmask_b32_e32 v22, v217, v22, vcc
	v_cmp_le_i32_e32 vcc, 40, v52
	v_cndmask_b32_e32 v38, v217, v38, vcc
	v_cmp_le_i32_e32 vcc, 9, v52
	v_cndmask_b32_e32 v23, v217, v23, vcc
	v_cmp_le_i32_e32 vcc, 41, v52
	v_cndmask_b32_e32 v39, v217, v39, vcc
	v_cmp_le_i32_e32 vcc, 10, v52
	v_cndmask_b32_e32 v24, v217, v24, vcc
	v_cmp_le_i32_e32 vcc, 42, v52
	v_cndmask_b32_e32 v40, v217, v40, vcc
	v_cmp_le_i32_e32 vcc, 11, v52
	v_cndmask_b32_e32 v25, v217, v25, vcc
	v_cmp_le_i32_e32 vcc, 43, v52
	v_cndmask_b32_e32 v41, v217, v41, vcc
	v_cmp_le_i32_e32 vcc, 16, v52
	v_cndmask_b32_e32 v26, v217, v26, vcc
	v_cmp_le_i32_e32 vcc, 48, v52
	v_cndmask_b32_e32 v42, v217, v42, vcc
	v_cmp_le_i32_e32 vcc, 17, v52
	v_cndmask_b32_e32 v27, v217, v27, vcc
	v_cmp_le_i32_e32 vcc, 49, v52
	v_cndmask_b32_e32 v43, v217, v43, vcc
	v_cmp_le_i32_e32 vcc, 18, v52
	v_cndmask_b32_e32 v28, v217, v28, vcc
	v_cmp_le_i32_e32 vcc, 50, v52
	v_cndmask_b32_e32 v44, v217, v44, vcc
	v_cmp_le_i32_e32 vcc, 19, v52
	v_cndmask_b32_e32 v29, v217, v29, vcc
	v_cmp_le_i32_e32 vcc, 51, v52
	v_cndmask_b32_e32 v45, v217, v45, vcc
	v_cmp_le_i32_e32 vcc, 24, v52
	v_cndmask_b32_e32 v30, v217, v30, vcc
	v_cmp_le_i32_e32 vcc, 56, v52
	v_cndmask_b32_e32 v46, v217, v46, vcc
	v_cmp_le_i32_e32 vcc, 25, v52
	v_cndmask_b32_e32 v31, v217, v31, vcc
	v_cmp_le_i32_e32 vcc, 57, v52
	v_cndmask_b32_e32 v47, v217, v47, vcc
	v_cmp_le_i32_e32 vcc, 26, v52
	v_cndmask_b32_e32 v32, v217, v32, vcc
	v_cmp_le_i32_e32 vcc, 58, v52
	v_cndmask_b32_e32 v48, v217, v48, vcc
	v_cmp_le_i32_e32 vcc, 27, v52
	v_cndmask_b32_e32 v33, v217, v33, vcc
	v_cmp_le_i32_e32 vcc, 59, v52
	v_cndmask_b32_e32 v49, v217, v49, vcc
